# v18 + odd_gate row loop rewritten: loads kept 2 units ahead in 3 rotating register sets, counted vmcnt, g resident, DPP reduction (was 4 serialized vmcnt(0) round trips per row)
# speedup vs baseline: 1.0062x; 1.0062x over previous
; DI F8 ldb8(const bf16_t* p) { return unpack8(*(const uint4*)p); }
; DI void stb8(bf16_t* p, const F8& f) { *(uint4*)p = pack8(f); }
; DI float gsum16(float v) { v += __shfl_xor(v, 8); v += __shfl_xor(v, 4); v += __shfl_xor(v, 2); v += __shfl_xor(v, 1); return v; }
; DI float siluf(float x) { return x / (1.f + __expf(-x)); }
; DI int tidx() { int t = threadIdx.x; asm volatile("" : "+v"(t)); return t; }
; DI int bidx() { int b = blockIdx.x; asm volatile("" : "+s"(b)); return b; }
; DI int gdim() { int g = gridDim.x; asm volatile("" : "+s"(g)); return g; }
; DI void odd_gate(const Params& p, int o) {
;     bf16_t* OB = (bf16_t*)(p.ws + WS_R1);
;     const bf16_t* ZAB = (const bf16_t*)p.out;
;     const float* go = p.in[19] + o * 128;
;     const int lane = tidx() & 63, gw = (bidx() * NT + tidx()) >> 6, nw = (gdim() * NT) >> 6;
;     for (int r = gw; r < MT; r += nw) {
; #pragma unroll
;         for (int it = 0; it < 2; ++it) {
;             const int c = it * 512 + lane * 8;
;             F8 x = ldb8(OB + (size_t)r * 1024 + c); const F8 z = ldb8(ZAB + (size_t)r * 1152 + c), gg = ldf8(go + (c & 127));
;             float ss = 0.f;
;             for (int k = 0; k < 8; ++k) ss += x.v[k] * x.v[k];
;             const float rs = rsqrtf(gsum16(ss) * (1.f / 128.f) + EPS);
;             for (int k = 0; k < 8; ++k) x.v[k] = x.v[k] * rs * gg.v[k] * siluf(z.v[k]);
;             stb8(OB + (size_t)r * 1024 + c, x);
;         }
.LBB0_425:
	s_mov_b32 s26, 0x3c000000
	v_readfirstlane_b32 s22, v8
	v_lshlrev_b32_e32 v16, 11, v8
	v_mul_u32_u24_e32 v26, 0x900, v8
	v_add_u32_e32 v16, v16, v212
	v_add_u32_e32 v26, v26, v212
	v_add_u32_e32 v16, 0x7800000, v16
	s_lshl_b32 s36, s14, 1
	s_lshl_b32 s37, s18, 1
	global_load_dwordx4 v[4:7], v[10:11], off
	global_load_dwordx4 v[0:3], v[10:11], off offset:16
	global_load_dwordx4 v[18:21], v16, s[62:63]
	global_load_dwordx4 v[22:25], v26, s[60:61]
	global_load_dwordx4 v[28:31], v16, s[62:63] offset:1024
	global_load_dwordx4 v[32:35], v26, s[60:61] offset:1024
	v_add_u32_e32 v17, s14, v16
	v_add_u32_e32 v27, s18, v26
	global_load_dwordx4 v[36:39], v17, s[62:63]
	global_load_dwordx4 v[46:49], v27, s[60:61]
	s_waitcnt vmcnt(0)
.Lodg_loop:
	s_waitcnt vmcnt(6)
	v_lshlrev_b32_e32 v50, 16, v18
	v_and_b32_e32 v51, 0xffff0000, v18
	v_lshlrev_b32_e32 v52, 16, v19
	v_and_b32_e32 v53, 0xffff0000, v19
	v_lshlrev_b32_e32 v54, 16, v20
	v_and_b32_e32 v55, 0xffff0000, v20
	v_lshlrev_b32_e32 v56, 16, v21
	v_and_b32_e32 v57, 0xffff0000, v21
	v_pk_mul_f32 v[58:59], v[50:51], v[50:51]
	v_lshlrev_b32_e32 v62, 16, v22
	v_pk_fma_f32 v[58:59], v[52:53], v[52:53], v[58:59]
	v_and_b32_e32 v63, 0xffff0000, v22
	v_pk_fma_f32 v[58:59], v[54:55], v[54:55], v[58:59]
	s_nop 0
	v_pk_fma_f32 v[58:59], v[56:57], v[56:57], v[58:59]
	s_nop 0
	v_add_f32_e32 v40, v58, v59
	s_nop 1
	v_add_f32_dpp v40, v40, v40 row_ror:8 row_mask:0xf bank_mask:0xf
	s_nop 1
	v_add_f32_dpp v40, v40, v40 row_ror:4 row_mask:0xf bank_mask:0xf
	s_nop 1
	v_add_f32_dpp v40, v40, v40 row_ror:2 row_mask:0xf bank_mask:0xf
	s_nop 1
	v_add_f32_dpp v40, v40, v40 row_ror:1 row_mask:0xf bank_mask:0xf
	v_fma_f32 v40, v40, s26, v64
	v_rsq_f32_e32 v40, v40
	v_mul_f32_e32 v60, 0xbfb8aa3b, v62
	v_mul_f32_e32 v61, 0xbfb8aa3b, v63
	v_exp_f32_e32 v60, v60
	v_exp_f32_e32 v61, v61
	v_pk_mul_f32 v[50:51], v[40:41], v[50:51] op_sel_hi:[0,1]
	v_pk_add_f32 v[60:61], v[60:61], 1.0 op_sel_hi:[1,0]
	v_pk_mul_f32 v[50:51], v[4:5], v[50:51]
	v_rcp_f32_e32 v60, v60
	v_rcp_f32_e32 v61, v61
	s_nop 0
	v_pk_mul_f32 v[62:63], v[62:63], v[60:61]
	s_nop 0
	v_pk_mul_f32 v[50:51], v[62:63], v[50:51]
	v_lshlrev_b32_e32 v58, 16, v23
	v_and_b32_e32 v59, 0xffff0000, v23
	v_mul_f32_e32 v60, 0xbfb8aa3b, v58
	v_mul_f32_e32 v61, 0xbfb8aa3b, v59
	v_exp_f32_e32 v60, v60
	v_exp_f32_e32 v61, v61
	v_pk_mul_f32 v[52:53], v[40:41], v[52:53] op_sel_hi:[0,1]
	v_pk_add_f32 v[60:61], v[60:61], 1.0 op_sel_hi:[1,0]
	v_pk_mul_f32 v[52:53], v[6:7], v[52:53]
	v_rcp_f32_e32 v60, v60
	v_rcp_f32_e32 v61, v61
	s_nop 0
	v_pk_mul_f32 v[58:59], v[58:59], v[60:61]
	s_nop 0
	v_pk_mul_f32 v[52:53], v[58:59], v[52:53]
	v_lshlrev_b32_e32 v58, 16, v24
	v_and_b32_e32 v59, 0xffff0000, v24
	v_mul_f32_e32 v60, 0xbfb8aa3b, v58
	v_mul_f32_e32 v61, 0xbfb8aa3b, v59
	v_exp_f32_e32 v60, v60
	v_exp_f32_e32 v61, v61
	v_pk_mul_f32 v[54:55], v[40:41], v[54:55] op_sel_hi:[0,1]
	v_pk_add_f32 v[60:61], v[60:61], 1.0 op_sel_hi:[1,0]
	v_pk_mul_f32 v[54:55], v[0:1], v[54:55]
	v_rcp_f32_e32 v60, v60
	v_rcp_f32_e32 v61, v61
	s_nop 0
	v_pk_mul_f32 v[58:59], v[58:59], v[60:61]
	s_nop 0
	v_pk_mul_f32 v[54:55], v[58:59], v[54:55]
	v_lshlrev_b32_e32 v58, 16, v25
	v_and_b32_e32 v59, 0xffff0000, v25
	v_mul_f32_e32 v60, 0xbfb8aa3b, v58
	v_mul_f32_e32 v61, 0xbfb8aa3b, v59
	v_exp_f32_e32 v60, v60
	v_exp_f32_e32 v61, v61
	v_pk_mul_f32 v[56:57], v[40:41], v[56:57] op_sel_hi:[0,1]
	v_pk_add_f32 v[60:61], v[60:61], 1.0 op_sel_hi:[1,0]
	v_pk_mul_f32 v[56:57], v[2:3], v[56:57]
	v_rcp_f32_e32 v60, v60
	v_rcp_f32_e32 v61, v61
	s_nop 0
	v_pk_mul_f32 v[58:59], v[58:59], v[60:61]
	s_nop 0
	v_pk_mul_f32 v[56:57], v[58:59], v[56:57]
	s_nop 0
	v_cvt_pk_bf16_f32 v58, v50, v51
	v_cvt_pk_bf16_f32 v59, v52, v53
	v_cvt_pk_bf16_f32 v60, v54, v55
	v_cvt_pk_bf16_f32 v61, v56, v57
	global_store_dwordx4 v16, v[58:61], s[62:63]
	v_add_u32_e32 v17, s14, v16
	v_add_u32_e32 v27, s18, v26
	global_load_dwordx4 v[18:21], v17, s[62:63] offset:1024
	global_load_dwordx4 v[22:25], v27, s[60:61] offset:1024
	s_waitcnt vmcnt(6)
	v_lshlrev_b32_e32 v50, 16, v28
	v_and_b32_e32 v51, 0xffff0000, v28
	v_lshlrev_b32_e32 v52, 16, v29
	v_and_b32_e32 v53, 0xffff0000, v29
	v_lshlrev_b32_e32 v54, 16, v30
	v_and_b32_e32 v55, 0xffff0000, v30
	v_lshlrev_b32_e32 v56, 16, v31
	v_and_b32_e32 v57, 0xffff0000, v31
	v_pk_mul_f32 v[58:59], v[50:51], v[50:51]
	v_lshlrev_b32_e32 v62, 16, v32
	v_pk_fma_f32 v[58:59], v[52:53], v[52:53], v[58:59]
	v_and_b32_e32 v63, 0xffff0000, v32
	v_pk_fma_f32 v[58:59], v[54:55], v[54:55], v[58:59]
	s_nop 0
	v_pk_fma_f32 v[58:59], v[56:57], v[56:57], v[58:59]
	s_nop 0
	v_add_f32_e32 v40, v58, v59
	s_nop 1
	v_add_f32_dpp v40, v40, v40 row_ror:8 row_mask:0xf bank_mask:0xf
	s_nop 1
	v_add_f32_dpp v40, v40, v40 row_ror:4 row_mask:0xf bank_mask:0xf
	s_nop 1
	v_add_f32_dpp v40, v40, v40 row_ror:2 row_mask:0xf bank_mask:0xf
	s_nop 1
	v_add_f32_dpp v40, v40, v40 row_ror:1 row_mask:0xf bank_mask:0xf
	v_fma_f32 v40, v40, s26, v64
	v_rsq_f32_e32 v40, v40
	v_mul_f32_e32 v60, 0xbfb8aa3b, v62
	v_mul_f32_e32 v61, 0xbfb8aa3b, v63
	v_exp_f32_e32 v60, v60
	v_exp_f32_e32 v61, v61
	v_pk_mul_f32 v[50:51], v[40:41], v[50:51] op_sel_hi:[0,1]
	v_pk_add_f32 v[60:61], v[60:61], 1.0 op_sel_hi:[1,0]
	v_pk_mul_f32 v[50:51], v[4:5], v[50:51]
	v_rcp_f32_e32 v60, v60
	v_rcp_f32_e32 v61, v61
	s_nop 0
	v_pk_mul_f32 v[62:63], v[62:63], v[60:61]
	s_nop 0
	v_pk_mul_f32 v[50:51], v[62:63], v[50:51]
	v_lshlrev_b32_e32 v58, 16, v33
	v_and_b32_e32 v59, 0xffff0000, v33
	v_mul_f32_e32 v60, 0xbfb8aa3b, v58
	v_mul_f32_e32 v61, 0xbfb8aa3b, v59
	v_exp_f32_e32 v60, v60
	v_exp_f32_e32 v61, v61
	v_pk_mul_f32 v[52:53], v[40:41], v[52:53] op_sel_hi:[0,1]
; DI F8 ldb8(const bf16_t* p) { return unpack8(*(const uint4*)p); }
; DI void stb8(bf16_t* p, const F8& f) { *(uint4*)p = pack8(f); }
; DI float gsum16(float v) { v += __shfl_xor(v, 8); v += __shfl_xor(v, 4); v += __shfl_xor(v, 2); v += __shfl_xor(v, 1); return v; }
; DI float siluf(float x) { return x / (1.f + __expf(-x)); }
; DI void odd_gate(const Params& p, int o) {
;     ...
;     for (int r = gw; r < MT; r += nw) {
; #pragma unroll
;         for (int it = 0; it < 2; ++it) {
;             const int c = it * 512 + lane * 8;
;             F8 x = ldb8(OB + (size_t)r * 1024 + c); const F8 z = ldb8(ZAB + (size_t)r * 1152 + c), gg = ldf8(go + (c & 127));
;             float ss = 0.f;
;             for (int k = 0; k < 8; ++k) ss += x.v[k] * x.v[k];
;             const float rs = rsqrtf(gsum16(ss) * (1.f / 128.f) + EPS);
;             for (int k = 0; k < 8; ++k) x.v[k] = x.v[k] * rs * gg.v[k] * siluf(z.v[k]);
;             stb8(OB + (size_t)r * 1024 + c, x);
;         }
	v_pk_add_f32 v[60:61], v[60:61], 1.0 op_sel_hi:[1,0]
	v_pk_mul_f32 v[52:53], v[6:7], v[52:53]
	v_rcp_f32_e32 v60, v60
	v_rcp_f32_e32 v61, v61
	s_nop 0
	v_pk_mul_f32 v[58:59], v[58:59], v[60:61]
	s_nop 0
	v_pk_mul_f32 v[52:53], v[58:59], v[52:53]
	v_lshlrev_b32_e32 v58, 16, v34
	v_and_b32_e32 v59, 0xffff0000, v34
	v_mul_f32_e32 v60, 0xbfb8aa3b, v58
	v_mul_f32_e32 v61, 0xbfb8aa3b, v59
	v_exp_f32_e32 v60, v60
	v_exp_f32_e32 v61, v61
	v_pk_mul_f32 v[54:55], v[40:41], v[54:55] op_sel_hi:[0,1]
	v_pk_add_f32 v[60:61], v[60:61], 1.0 op_sel_hi:[1,0]
	v_pk_mul_f32 v[54:55], v[0:1], v[54:55]
	v_rcp_f32_e32 v60, v60
	v_rcp_f32_e32 v61, v61
	s_nop 0
	v_pk_mul_f32 v[58:59], v[58:59], v[60:61]
	s_nop 0
	v_pk_mul_f32 v[54:55], v[58:59], v[54:55]
	v_lshlrev_b32_e32 v58, 16, v35
	v_and_b32_e32 v59, 0xffff0000, v35
	v_mul_f32_e32 v60, 0xbfb8aa3b, v58
	v_mul_f32_e32 v61, 0xbfb8aa3b, v59
	v_exp_f32_e32 v60, v60
	v_exp_f32_e32 v61, v61
	v_pk_mul_f32 v[56:57], v[40:41], v[56:57] op_sel_hi:[0,1]
	v_pk_add_f32 v[60:61], v[60:61], 1.0 op_sel_hi:[1,0]
	v_pk_mul_f32 v[56:57], v[2:3], v[56:57]
	v_rcp_f32_e32 v60, v60
	v_rcp_f32_e32 v61, v61
	s_nop 0
	v_pk_mul_f32 v[58:59], v[58:59], v[60:61]
	s_nop 0
	v_pk_mul_f32 v[56:57], v[58:59], v[56:57]
	s_nop 0
	v_cvt_pk_bf16_f32 v58, v50, v51
	v_cvt_pk_bf16_f32 v59, v52, v53
	v_cvt_pk_bf16_f32 v60, v54, v55
	v_cvt_pk_bf16_f32 v61, v56, v57
	global_store_dwordx4 v16, v[58:61], s[62:63] offset:1024
	v_add_u32_e32 v17, s36, v16
	v_add_u32_e32 v27, s37, v26
	global_load_dwordx4 v[28:31], v17, s[62:63]
	global_load_dwordx4 v[32:35], v27, s[60:61]
	s_add_i32 s22, s22, s6
	v_add_u32_e32 v16, s14, v16
	v_add_u32_e32 v26, s18, v26
	s_cmp_gt_i32 s22, s30
	s_cbranch_scc1 .LBB0_426
	s_waitcnt vmcnt(6)
	v_lshlrev_b32_e32 v50, 16, v36
	v_and_b32_e32 v51, 0xffff0000, v36
	v_lshlrev_b32_e32 v52, 16, v37
	v_and_b32_e32 v53, 0xffff0000, v37
	v_lshlrev_b32_e32 v54, 16, v38
	v_and_b32_e32 v55, 0xffff0000, v38
	v_lshlrev_b32_e32 v56, 16, v39
	v_and_b32_e32 v57, 0xffff0000, v39
	v_pk_mul_f32 v[58:59], v[50:51], v[50:51]
	v_lshlrev_b32_e32 v62, 16, v46
	v_pk_fma_f32 v[58:59], v[52:53], v[52:53], v[58:59]
	v_and_b32_e32 v63, 0xffff0000, v46
	v_pk_fma_f32 v[58:59], v[54:55], v[54:55], v[58:59]
	s_nop 0
	v_pk_fma_f32 v[58:59], v[56:57], v[56:57], v[58:59]
	s_nop 0
	v_add_f32_e32 v40, v58, v59
	s_nop 1
	v_add_f32_dpp v40, v40, v40 row_ror:8 row_mask:0xf bank_mask:0xf
	s_nop 1
	v_add_f32_dpp v40, v40, v40 row_ror:4 row_mask:0xf bank_mask:0xf
	s_nop 1
	v_add_f32_dpp v40, v40, v40 row_ror:2 row_mask:0xf bank_mask:0xf
	s_nop 1
	v_add_f32_dpp v40, v40, v40 row_ror:1 row_mask:0xf bank_mask:0xf
	v_fma_f32 v40, v40, s26, v64
	v_rsq_f32_e32 v40, v40
	v_mul_f32_e32 v60, 0xbfb8aa3b, v62
	v_mul_f32_e32 v61, 0xbfb8aa3b, v63
	v_exp_f32_e32 v60, v60
	v_exp_f32_e32 v61, v61
	v_pk_mul_f32 v[50:51], v[40:41], v[50:51] op_sel_hi:[0,1]
	v_pk_add_f32 v[60:61], v[60:61], 1.0 op_sel_hi:[1,0]
	v_pk_mul_f32 v[50:51], v[4:5], v[50:51]
	v_rcp_f32_e32 v60, v60
	v_rcp_f32_e32 v61, v61
	s_nop 0
	v_pk_mul_f32 v[62:63], v[62:63], v[60:61]
	s_nop 0
	v_pk_mul_f32 v[50:51], v[62:63], v[50:51]
	v_lshlrev_b32_e32 v58, 16, v47
	v_and_b32_e32 v59, 0xffff0000, v47
	v_mul_f32_e32 v60, 0xbfb8aa3b, v58
	v_mul_f32_e32 v61, 0xbfb8aa3b, v59
	v_exp_f32_e32 v60, v60
	v_exp_f32_e32 v61, v61
	v_pk_mul_f32 v[52:53], v[40:41], v[52:53] op_sel_hi:[0,1]
	v_pk_add_f32 v[60:61], v[60:61], 1.0 op_sel_hi:[1,0]
	v_pk_mul_f32 v[52:53], v[6:7], v[52:53]
	v_rcp_f32_e32 v60, v60
	v_rcp_f32_e32 v61, v61
	s_nop 0
	v_pk_mul_f32 v[58:59], v[58:59], v[60:61]
	s_nop 0
	v_pk_mul_f32 v[52:53], v[58:59], v[52:53]
	v_lshlrev_b32_e32 v58, 16, v48
	v_and_b32_e32 v59, 0xffff0000, v48
	v_mul_f32_e32 v60, 0xbfb8aa3b, v58
	v_mul_f32_e32 v61, 0xbfb8aa3b, v59
	v_exp_f32_e32 v60, v60
	v_exp_f32_e32 v61, v61
	v_pk_mul_f32 v[54:55], v[40:41], v[54:55] op_sel_hi:[0,1]
	v_pk_add_f32 v[60:61], v[60:61], 1.0 op_sel_hi:[1,0]
	v_pk_mul_f32 v[54:55], v[0:1], v[54:55]
	v_rcp_f32_e32 v60, v60
	v_rcp_f32_e32 v61, v61
	s_nop 0
	v_pk_mul_f32 v[58:59], v[58:59], v[60:61]
	s_nop 0
	v_pk_mul_f32 v[54:55], v[58:59], v[54:55]
	v_lshlrev_b32_e32 v58, 16, v49
	v_and_b32_e32 v59, 0xffff0000, v49
	v_mul_f32_e32 v60, 0xbfb8aa3b, v58
	v_mul_f32_e32 v61, 0xbfb8aa3b, v59
	v_exp_f32_e32 v60, v60
	v_exp_f32_e32 v61, v61
	v_pk_mul_f32 v[56:57], v[40:41], v[56:57] op_sel_hi:[0,1]
	v_pk_add_f32 v[60:61], v[60:61], 1.0 op_sel_hi:[1,0]
	v_pk_mul_f32 v[56:57], v[2:3], v[56:57]
	v_rcp_f32_e32 v60, v60
	v_rcp_f32_e32 v61, v61
	s_nop 0
	v_pk_mul_f32 v[58:59], v[58:59], v[60:61]
	s_nop 0
	v_pk_mul_f32 v[56:57], v[58:59], v[56:57]
	s_nop 0
	v_cvt_pk_bf16_f32 v58, v50, v51
	v_cvt_pk_bf16_f32 v59, v52, v53
	v_cvt_pk_bf16_f32 v60, v54, v55
	v_cvt_pk_bf16_f32 v61, v56, v57
	global_store_dwordx4 v16, v[58:61], s[62:63]
	v_add_u32_e32 v17, s14, v16
	v_add_u32_e32 v27, s18, v26
	global_load_dwordx4 v[36:39], v17, s[62:63] offset:1024
	global_load_dwordx4 v[46:49], v27, s[60:61] offset:1024
	s_waitcnt vmcnt(6)
; DI F8 ldb8(const bf16_t* p) { return unpack8(*(const uint4*)p); }
; DI void stb8(bf16_t* p, const F8& f) { *(uint4*)p = pack8(f); }
; DI float gsum16(float v) { v += __shfl_xor(v, 8); v += __shfl_xor(v, 4); v += __shfl_xor(v, 2); v += __shfl_xor(v, 1); return v; }
; DI float siluf(float x) { return x / (1.f + __expf(-x)); }
; DI void odd_gate(const Params& p, int o) {
;     ...
;     for (int r = gw; r < MT; r += nw) {
; #pragma unroll
;         for (int it = 0; it < 2; ++it) {
;             const int c = it * 512 + lane * 8;
;             F8 x = ldb8(OB + (size_t)r * 1024 + c); const F8 z = ldb8(ZAB + (size_t)r * 1152 + c), gg = ldf8(go + (c & 127));
;             float ss = 0.f;
;             for (int k = 0; k < 8; ++k) ss += x.v[k] * x.v[k];
;             const float rs = rsqrtf(gsum16(ss) * (1.f / 128.f) + EPS);
;             for (int k = 0; k < 8; ++k) x.v[k] = x.v[k] * rs * gg.v[k] * siluf(z.v[k]);
;             stb8(OB + (size_t)r * 1024 + c, x);
;         }
	v_lshlrev_b32_e32 v50, 16, v18
	v_and_b32_e32 v51, 0xffff0000, v18
	v_lshlrev_b32_e32 v52, 16, v19
	v_and_b32_e32 v53, 0xffff0000, v19
	v_lshlrev_b32_e32 v54, 16, v20
	v_and_b32_e32 v55, 0xffff0000, v20
	v_lshlrev_b32_e32 v56, 16, v21
	v_and_b32_e32 v57, 0xffff0000, v21
	v_pk_mul_f32 v[58:59], v[50:51], v[50:51]
	v_lshlrev_b32_e32 v62, 16, v22
	v_pk_fma_f32 v[58:59], v[52:53], v[52:53], v[58:59]
	v_and_b32_e32 v63, 0xffff0000, v22
	v_pk_fma_f32 v[58:59], v[54:55], v[54:55], v[58:59]
	s_nop 0
	v_pk_fma_f32 v[58:59], v[56:57], v[56:57], v[58:59]
	s_nop 0
	v_add_f32_e32 v40, v58, v59
	s_nop 1
	v_add_f32_dpp v40, v40, v40 row_ror:8 row_mask:0xf bank_mask:0xf
	s_nop 1
	v_add_f32_dpp v40, v40, v40 row_ror:4 row_mask:0xf bank_mask:0xf
	s_nop 1
	v_add_f32_dpp v40, v40, v40 row_ror:2 row_mask:0xf bank_mask:0xf
	s_nop 1
	v_add_f32_dpp v40, v40, v40 row_ror:1 row_mask:0xf bank_mask:0xf
	v_fma_f32 v40, v40, s26, v64
	v_rsq_f32_e32 v40, v40
	v_mul_f32_e32 v60, 0xbfb8aa3b, v62
	v_mul_f32_e32 v61, 0xbfb8aa3b, v63
	v_exp_f32_e32 v60, v60
	v_exp_f32_e32 v61, v61
	v_pk_mul_f32 v[50:51], v[40:41], v[50:51] op_sel_hi:[0,1]
	v_pk_add_f32 v[60:61], v[60:61], 1.0 op_sel_hi:[1,0]
	v_pk_mul_f32 v[50:51], v[4:5], v[50:51]
	v_rcp_f32_e32 v60, v60
	v_rcp_f32_e32 v61, v61
	s_nop 0
	v_pk_mul_f32 v[62:63], v[62:63], v[60:61]
	s_nop 0
	v_pk_mul_f32 v[50:51], v[62:63], v[50:51]
	v_lshlrev_b32_e32 v58, 16, v23
	v_and_b32_e32 v59, 0xffff0000, v23
	v_mul_f32_e32 v60, 0xbfb8aa3b, v58
	v_mul_f32_e32 v61, 0xbfb8aa3b, v59
	v_exp_f32_e32 v60, v60
	v_exp_f32_e32 v61, v61
	v_pk_mul_f32 v[52:53], v[40:41], v[52:53] op_sel_hi:[0,1]
	v_pk_add_f32 v[60:61], v[60:61], 1.0 op_sel_hi:[1,0]
	v_pk_mul_f32 v[52:53], v[6:7], v[52:53]
	v_rcp_f32_e32 v60, v60
	v_rcp_f32_e32 v61, v61
	s_nop 0
	v_pk_mul_f32 v[58:59], v[58:59], v[60:61]
	s_nop 0
	v_pk_mul_f32 v[52:53], v[58:59], v[52:53]
	v_lshlrev_b32_e32 v58, 16, v24
	v_and_b32_e32 v59, 0xffff0000, v24
	v_mul_f32_e32 v60, 0xbfb8aa3b, v58
	v_mul_f32_e32 v61, 0xbfb8aa3b, v59
	v_exp_f32_e32 v60, v60
	v_exp_f32_e32 v61, v61
	v_pk_mul_f32 v[54:55], v[40:41], v[54:55] op_sel_hi:[0,1]
	v_pk_add_f32 v[60:61], v[60:61], 1.0 op_sel_hi:[1,0]
	v_pk_mul_f32 v[54:55], v[0:1], v[54:55]
	v_rcp_f32_e32 v60, v60
	v_rcp_f32_e32 v61, v61
	s_nop 0
	v_pk_mul_f32 v[58:59], v[58:59], v[60:61]
	s_nop 0
	v_pk_mul_f32 v[54:55], v[58:59], v[54:55]
	v_lshlrev_b32_e32 v58, 16, v25
	v_and_b32_e32 v59, 0xffff0000, v25
	v_mul_f32_e32 v60, 0xbfb8aa3b, v58
	v_mul_f32_e32 v61, 0xbfb8aa3b, v59
	v_exp_f32_e32 v60, v60
	v_exp_f32_e32 v61, v61
	v_pk_mul_f32 v[56:57], v[40:41], v[56:57] op_sel_hi:[0,1]
	v_pk_add_f32 v[60:61], v[60:61], 1.0 op_sel_hi:[1,0]
	v_pk_mul_f32 v[56:57], v[2:3], v[56:57]
	v_rcp_f32_e32 v60, v60
	v_rcp_f32_e32 v61, v61
	s_nop 0
	v_pk_mul_f32 v[58:59], v[58:59], v[60:61]
	s_nop 0
	v_pk_mul_f32 v[56:57], v[58:59], v[56:57]
	s_nop 0
	v_cvt_pk_bf16_f32 v58, v50, v51
	v_cvt_pk_bf16_f32 v59, v52, v53
	v_cvt_pk_bf16_f32 v60, v54, v55
	v_cvt_pk_bf16_f32 v61, v56, v57
	global_store_dwordx4 v16, v[58:61], s[62:63] offset:1024
	v_add_u32_e32 v17, s36, v16
	v_add_u32_e32 v27, s37, v26
	global_load_dwordx4 v[18:21], v17, s[62:63]
	global_load_dwordx4 v[22:25], v27, s[60:61]
	s_add_i32 s22, s22, s6
	v_add_u32_e32 v16, s14, v16
	v_add_u32_e32 v26, s18, v26
	s_cmp_gt_i32 s22, s30
	s_cbranch_scc1 .LBB0_426
; DI F8 ldb8(const bf16_t* p) { return unpack8(*(const uint4*)p); }
; DI void stb8(bf16_t* p, const F8& f) { *(uint4*)p = pack8(f); }
; DI float gsum16(float v) { v += __shfl_xor(v, 8); v += __shfl_xor(v, 4); v += __shfl_xor(v, 2); v += __shfl_xor(v, 1); return v; }
; DI float siluf(float x) { return x / (1.f + __expf(-x)); }
; DI void odd_gate(const Params& p, int o) {
;     ...
;     for (int r = gw; r < MT; r += nw) {
; #pragma unroll
;         for (int it = 0; it < 2; ++it) {
;             const int c = it * 512 + lane * 8;
;             F8 x = ldb8(OB + (size_t)r * 1024 + c); const F8 z = ldb8(ZAB + (size_t)r * 1152 + c), gg = ldf8(go + (c & 127));
;             float ss = 0.f;
;             for (int k = 0; k < 8; ++k) ss += x.v[k] * x.v[k];
;             const float rs = rsqrtf(gsum16(ss) * (1.f / 128.f) + EPS);
;             for (int k = 0; k < 8; ++k) x.v[k] = x.v[k] * rs * gg.v[k] * siluf(z.v[k]);
;             stb8(OB + (size_t)r * 1024 + c, x);
;         }
	s_waitcnt vmcnt(6)
	v_lshlrev_b32_e32 v50, 16, v28
	v_and_b32_e32 v51, 0xffff0000, v28
	v_lshlrev_b32_e32 v52, 16, v29
	v_and_b32_e32 v53, 0xffff0000, v29
	v_lshlrev_b32_e32 v54, 16, v30
	v_and_b32_e32 v55, 0xffff0000, v30
	v_lshlrev_b32_e32 v56, 16, v31
	v_and_b32_e32 v57, 0xffff0000, v31
	v_pk_mul_f32 v[58:59], v[50:51], v[50:51]
	v_lshlrev_b32_e32 v62, 16, v32
	v_pk_fma_f32 v[58:59], v[52:53], v[52:53], v[58:59]
	v_and_b32_e32 v63, 0xffff0000, v32
	v_pk_fma_f32 v[58:59], v[54:55], v[54:55], v[58:59]
	s_nop 0
	v_pk_fma_f32 v[58:59], v[56:57], v[56:57], v[58:59]
	s_nop 0
	v_add_f32_e32 v40, v58, v59
	s_nop 1
	v_add_f32_dpp v40, v40, v40 row_ror:8 row_mask:0xf bank_mask:0xf
	s_nop 1
	v_add_f32_dpp v40, v40, v40 row_ror:4 row_mask:0xf bank_mask:0xf
	s_nop 1
	v_add_f32_dpp v40, v40, v40 row_ror:2 row_mask:0xf bank_mask:0xf
	s_nop 1
	v_add_f32_dpp v40, v40, v40 row_ror:1 row_mask:0xf bank_mask:0xf
	v_fma_f32 v40, v40, s26, v64
	v_rsq_f32_e32 v40, v40
	v_mul_f32_e32 v60, 0xbfb8aa3b, v62
	v_mul_f32_e32 v61, 0xbfb8aa3b, v63
	v_exp_f32_e32 v60, v60
	v_exp_f32_e32 v61, v61
	v_pk_mul_f32 v[50:51], v[40:41], v[50:51] op_sel_hi:[0,1]
	v_pk_add_f32 v[60:61], v[60:61], 1.0 op_sel_hi:[1,0]
	v_pk_mul_f32 v[50:51], v[4:5], v[50:51]
	v_rcp_f32_e32 v60, v60
	v_rcp_f32_e32 v61, v61
	s_nop 0
	v_pk_mul_f32 v[62:63], v[62:63], v[60:61]
	s_nop 0
	v_pk_mul_f32 v[50:51], v[62:63], v[50:51]
	v_lshlrev_b32_e32 v58, 16, v33
	v_and_b32_e32 v59, 0xffff0000, v33
	v_mul_f32_e32 v60, 0xbfb8aa3b, v58
	v_mul_f32_e32 v61, 0xbfb8aa3b, v59
	v_exp_f32_e32 v60, v60
	v_exp_f32_e32 v61, v61
	v_pk_mul_f32 v[52:53], v[40:41], v[52:53] op_sel_hi:[0,1]
	v_pk_add_f32 v[60:61], v[60:61], 1.0 op_sel_hi:[1,0]
	v_pk_mul_f32 v[52:53], v[6:7], v[52:53]
	v_rcp_f32_e32 v60, v60
	v_rcp_f32_e32 v61, v61
	s_nop 0
	v_pk_mul_f32 v[58:59], v[58:59], v[60:61]
	s_nop 0
	v_pk_mul_f32 v[52:53], v[58:59], v[52:53]
	v_lshlrev_b32_e32 v58, 16, v34
	v_and_b32_e32 v59, 0xffff0000, v34
	v_mul_f32_e32 v60, 0xbfb8aa3b, v58
	v_mul_f32_e32 v61, 0xbfb8aa3b, v59
	v_exp_f32_e32 v60, v60
	v_exp_f32_e32 v61, v61
	v_pk_mul_f32 v[54:55], v[40:41], v[54:55] op_sel_hi:[0,1]
	v_pk_add_f32 v[60:61], v[60:61], 1.0 op_sel_hi:[1,0]
	v_pk_mul_f32 v[54:55], v[0:1], v[54:55]
	v_rcp_f32_e32 v60, v60
	v_rcp_f32_e32 v61, v61
	s_nop 0
	v_pk_mul_f32 v[58:59], v[58:59], v[60:61]
	s_nop 0
	v_pk_mul_f32 v[54:55], v[58:59], v[54:55]
	v_lshlrev_b32_e32 v58, 16, v35
	v_and_b32_e32 v59, 0xffff0000, v35
	v_mul_f32_e32 v60, 0xbfb8aa3b, v58
	v_mul_f32_e32 v61, 0xbfb8aa3b, v59
	v_exp_f32_e32 v60, v60
	v_exp_f32_e32 v61, v61
	v_pk_mul_f32 v[56:57], v[40:41], v[56:57] op_sel_hi:[0,1]
	v_pk_add_f32 v[60:61], v[60:61], 1.0 op_sel_hi:[1,0]
	v_pk_mul_f32 v[56:57], v[2:3], v[56:57]
	v_rcp_f32_e32 v60, v60
	v_rcp_f32_e32 v61, v61
	s_nop 0
	v_pk_mul_f32 v[58:59], v[58:59], v[60:61]
	s_nop 0
	v_pk_mul_f32 v[56:57], v[58:59], v[56:57]
	s_nop 0
	v_cvt_pk_bf16_f32 v58, v50, v51
	v_cvt_pk_bf16_f32 v59, v52, v53
	v_cvt_pk_bf16_f32 v60, v54, v55
	v_cvt_pk_bf16_f32 v61, v56, v57
	global_store_dwordx4 v16, v[58:61], s[62:63]
	v_add_u32_e32 v17, s14, v16
	v_add_u32_e32 v27, s18, v26
	global_load_dwordx4 v[28:31], v17, s[62:63] offset:1024
	global_load_dwordx4 v[32:35], v27, s[60:61] offset:1024
	s_waitcnt vmcnt(6)
	v_lshlrev_b32_e32 v50, 16, v36
	v_and_b32_e32 v51, 0xffff0000, v36
	v_lshlrev_b32_e32 v52, 16, v37
	v_and_b32_e32 v53, 0xffff0000, v37
	v_lshlrev_b32_e32 v54, 16, v38
	v_and_b32_e32 v55, 0xffff0000, v38
	v_lshlrev_b32_e32 v56, 16, v39
	v_and_b32_e32 v57, 0xffff0000, v39
	v_pk_mul_f32 v[58:59], v[50:51], v[50:51]
	v_lshlrev_b32_e32 v62, 16, v46
	v_pk_fma_f32 v[58:59], v[52:53], v[52:53], v[58:59]
	v_and_b32_e32 v63, 0xffff0000, v46
	v_pk_fma_f32 v[58:59], v[54:55], v[54:55], v[58:59]
	s_nop 0
	v_pk_fma_f32 v[58:59], v[56:57], v[56:57], v[58:59]
	s_nop 0
	v_add_f32_e32 v40, v58, v59
	s_nop 1
	v_add_f32_dpp v40, v40, v40 row_ror:8 row_mask:0xf bank_mask:0xf
	s_nop 1
	v_add_f32_dpp v40, v40, v40 row_ror:4 row_mask:0xf bank_mask:0xf
	s_nop 1
	v_add_f32_dpp v40, v40, v40 row_ror:2 row_mask:0xf bank_mask:0xf
	s_nop 1
	v_add_f32_dpp v40, v40, v40 row_ror:1 row_mask:0xf bank_mask:0xf
	v_fma_f32 v40, v40, s26, v64
	v_rsq_f32_e32 v40, v40
	v_mul_f32_e32 v60, 0xbfb8aa3b, v62
	v_mul_f32_e32 v61, 0xbfb8aa3b, v63
	v_exp_f32_e32 v60, v60
	v_exp_f32_e32 v61, v61
	v_pk_mul_f32 v[50:51], v[40:41], v[50:51] op_sel_hi:[0,1]
	v_pk_add_f32 v[60:61], v[60:61], 1.0 op_sel_hi:[1,0]
	v_pk_mul_f32 v[50:51], v[4:5], v[50:51]
	v_rcp_f32_e32 v60, v60
	v_rcp_f32_e32 v61, v61
	s_nop 0
	v_pk_mul_f32 v[62:63], v[62:63], v[60:61]
	s_nop 0
	v_pk_mul_f32 v[50:51], v[62:63], v[50:51]
	v_lshlrev_b32_e32 v58, 16, v47
	v_and_b32_e32 v59, 0xffff0000, v47
	v_mul_f32_e32 v60, 0xbfb8aa3b, v58
	v_mul_f32_e32 v61, 0xbfb8aa3b, v59
	v_exp_f32_e32 v60, v60
	v_exp_f32_e32 v61, v61
	v_pk_mul_f32 v[52:53], v[40:41], v[52:53] op_sel_hi:[0,1]
	v_pk_add_f32 v[60:61], v[60:61], 1.0 op_sel_hi:[1,0]
	v_pk_mul_f32 v[52:53], v[6:7], v[52:53]
	v_rcp_f32_e32 v60, v60
	v_rcp_f32_e32 v61, v61
	s_nop 0
	v_pk_mul_f32 v[58:59], v[58:59], v[60:61]
	s_nop 0
	v_pk_mul_f32 v[52:53], v[58:59], v[52:53]
	v_lshlrev_b32_e32 v58, 16, v48
	v_and_b32_e32 v59, 0xffff0000, v48
	v_mul_f32_e32 v60, 0xbfb8aa3b, v58
	v_mul_f32_e32 v61, 0xbfb8aa3b, v59
	v_exp_f32_e32 v60, v60
	v_exp_f32_e32 v61, v61
	v_pk_mul_f32 v[54:55], v[40:41], v[54:55] op_sel_hi:[0,1]
	v_pk_add_f32 v[60:61], v[60:61], 1.0 op_sel_hi:[1,0]
	v_pk_mul_f32 v[54:55], v[0:1], v[54:55]
	v_rcp_f32_e32 v60, v60
	v_rcp_f32_e32 v61, v61
	s_nop 0
	v_pk_mul_f32 v[58:59], v[58:59], v[60:61]
	s_nop 0
	v_pk_mul_f32 v[54:55], v[58:59], v[54:55]
	v_lshlrev_b32_e32 v58, 16, v49
	v_and_b32_e32 v59, 0xffff0000, v49
	v_mul_f32_e32 v60, 0xbfb8aa3b, v58
	v_mul_f32_e32 v61, 0xbfb8aa3b, v59
	v_exp_f32_e32 v60, v60
	v_exp_f32_e32 v61, v61
	v_pk_mul_f32 v[56:57], v[40:41], v[56:57] op_sel_hi:[0,1]
	v_pk_add_f32 v[60:61], v[60:61], 1.0 op_sel_hi:[1,0]
	v_pk_mul_f32 v[56:57], v[2:3], v[56:57]
	v_rcp_f32_e32 v60, v60
	v_rcp_f32_e32 v61, v61
	s_nop 0
	v_pk_mul_f32 v[58:59], v[58:59], v[60:61]
	s_nop 0
	v_pk_mul_f32 v[56:57], v[58:59], v[56:57]
	s_nop 0
	v_cvt_pk_bf16_f32 v58, v50, v51
	v_cvt_pk_bf16_f32 v59, v52, v53
	v_cvt_pk_bf16_f32 v60, v54, v55
	v_cvt_pk_bf16_f32 v61, v56, v57
	global_store_dwordx4 v16, v[58:61], s[62:63] offset:1024
	v_add_u32_e32 v17, s36, v16
	v_add_u32_e32 v27, s37, v26
	global_load_dwordx4 v[36:39], v17, s[62:63]
	global_load_dwordx4 v[46:49], v27, s[60:61]
	s_add_i32 s22, s22, s6
	v_add_u32_e32 v16, s14, v16
	v_add_u32_e32 v26, s18, v26
	s_cmp_gt_i32 s22, s30
	s_cbranch_scc1 .LBB0_426
	s_branch .Lodg_loop
